# v36 plus P5 stagger: the 128 latent-unit workgroups (which have slack) start about 5 us later than the critical GLU class
# baseline (speedup 1.0000x reference)
.LBB0_360:
	s_or_b64 exec, exec, s[6:7]
	s_cmpk_gt_i32 s38, 0x7f
	s_cbranch_scc1 .Lslk5d
	s_sleep 127
	s_sleep 40
.Lslk5d:
	s_add_u32 s60, s54, 0xb800000
	s_addc_u32 s61, s55, 0
	s_cmpk_gt_i32 s38, 0x7f
	s_waitcnt lgkmcnt(0)
	s_barrier
	s_cbranch_scc0 .LBB0_365
	s_cmpk_lt_u32 s38, 0x80
	s_mov_b64 s[14:15], 0
	s_cbranch_scc0 .LBB0_366
	s_and_b32 s0, s38, 3
	s_lshl_b32 s1, s0, 2
	v_readlane_b32 s16, v242, 0
	v_mov_b32_e32 v4, v0
	v_mov_b32_e32 v1, s1
	v_readlane_b32 s20, v242, 4
	v_readlane_b32 s21, v242, 5
	s_nop 4
	global_load_dword v2, v1, s[20:21]
	global_load_dword v5, v1, s[20:21] offset:16
	s_mov_b32 s7, 0xbfb8aa3b
	s_mov_b32 s8, 0x42ce8ed0
	s_mov_b32 s9, 0xc2b17218
	v_mov_b32_e32 v8, 0x7f800000
	s_mov_b32 s10, 0x3f2aaaab
	s_mov_b32 s6, 0x3f317218
	v_mov_b32_e32 v9, 0x3ecc95a3
	s_mov_b32 s4, 0x7f800000
	s_mov_b32 s5, 0x33800000
	v_mov_b32_e32 v10, 0x3f2aaada
	s_lshl_b32 s1, s38, 6
	s_add_i32 s1, s1, 0x7fffe000
	v_readfirstlane_b32 s11, v4
	s_and_b32 s3, s1, 0x7fffff00
	s_ashr_i32 s1, s11, 6
	v_and_b32_e32 v12, 15, v4
	s_lshl_b32 s16, s0, 8
	v_readlane_b32 s18, v242, 2
	v_mov_b32_e32 v3, 0
	s_movk_i32 s18, 0x1400
	v_readlane_b32 s17, v242, 1
	s_mov_b32 s17, 0
	v_bfe_u32 v13, v4, 4, 2
	v_and_b32_e32 v1, 63, v4
	v_readlane_b32 s19, v242, 3
	v_readlane_b32 s22, v242, 6
	v_readlane_b32 s23, v242, 7
	v_readlane_b32 s24, v242, 8
	v_readlane_b32 s25, v242, 9
	v_readlane_b32 s26, v242, 10
	s_movk_i32 s19, 0xffee
	s_movk_i32 s20, 0xffed
	s_movk_i32 s21, 0xffdf
	s_movk_i32 s22, 0xffde
	s_movk_i32 s23, 0xffdd
	s_movk_i32 s24, 0xffcf
	s_movk_i32 s25, 0xffce
	s_movk_i32 s26, 0xffcd
	v_mov_b32_e32 v34, v3
	v_mov_b32_e32 v35, v3
	v_mov_b32_e32 v36, v3
	v_mov_b32_e32 v37, v3
	v_mov_b32_e32 v38, v3
	v_mov_b32_e32 v39, v3
	v_mov_b32_e32 v40, v3
	v_mov_b32_e32 v41, v3
	v_mov_b32_e32 v50, v3
	v_mov_b32_e32 v51, v3
	v_mov_b32_e32 v52, v3
	v_mov_b32_e32 v53, v3
	v_mov_b32_e32 v66, v3
	v_mov_b32_e32 v67, v3
	v_mov_b32_e32 v68, v3
	v_mov_b32_e32 v69, v3
	v_mov_b32_e32 v25, v3
	v_mov_b32_e32 v26, v3
	v_mov_b32_e32 v27, v3
	v_mov_b32_e32 v28, v3
	v_mov_b32_e32 v29, v3
	v_mov_b32_e32 v30, v3
	v_mov_b32_e32 v31, v3
	v_mov_b32_e32 v32, v3
	v_mov_b32_e32 v33, v3
	v_mov_b32_e32 v62, v3
	v_mov_b32_e32 v63, v3
	v_mov_b32_e32 v64, v3
	v_mov_b32_e32 v65, v3
	v_mov_b32_e32 v70, v3
	v_mov_b32_e32 v71, v3
	v_mov_b32_e32 v72, v3
	v_mov_b32_e32 v73, v3
	v_mov_b32_e32 v74, v3
	v_mov_b32_e32 v75, v3
	v_mov_b32_e32 v76, v3
	v_mov_b32_e32 v77, v3
	v_mov_b32_e32 v94, v3
	v_mov_b32_e32 v95, v3
	v_mov_b32_e32 v96, v3
	s_waitcnt vmcnt(1)
	v_mul_f32_e32 v6, 0xbfb8aa3b, v2
	v_fma_f32 v11, v2, s7, -v6
	v_rndne_f32_e32 v14, v6
	v_fmac_f32_e32 v11, 0xb2a5705f, v2
	v_sub_f32_e32 v6, v6, v14
	v_add_f32_e32 v6, v6, v11
	v_cvt_i32_f32_e32 v14, v14
	v_exp_f32_e32 v6, v6
	s_waitcnt vmcnt(0)
	v_mul_f32_e32 v7, 0xbfb8aa3b, v5
	v_cmp_nlt_f32_e32 vcc, s8, v2
	v_fma_f32 v15, v5, s7, -v7
	v_ldexp_f32 v6, v6, v14
	v_rndne_f32_e32 v16, v7
	v_cndmask_b32_e32 v6, 0, v6, vcc
	v_cmp_ngt_f32_e32 vcc, s9, v2
	v_fmac_f32_e32 v15, 0xb2a5705f, v5
	v_sub_f32_e32 v7, v7, v16
	v_cndmask_b32_e32 v2, v8, v6, vcc
	v_add_f32_e32 v7, v7, v15
	v_add_f32_e32 v14, 1.0, v2
	v_cvt_i32_f32_e32 v11, v16
	v_exp_f32_e32 v15, v7
	v_add_f32_e32 v16, -1.0, v14
	v_frexp_mant_f32_e32 v17, v14
	v_cvt_f64_f32_e32 v[6:7], v14
	v_sub_f32_e32 v18, v16, v14
	v_frexp_exp_i32_f64_e32 v6, v[6:7]
	v_cmp_gt_f32_e32 vcc, s10, v17
	v_sub_f32_e32 v16, v2, v16
	v_add_f32_e32 v7, 1.0, v18
	v_subbrev_co_u32_e32 v6, vcc, 0, v6, vcc
	v_add_f32_e32 v7, v16, v7
	v_sub_u32_e32 v16, 0, v6
	v_cvt_f32_i32_e32 v6, v6
	v_ldexp_f32 v14, v14, v16
	v_ldexp_f32 v7, v7, v16
	v_add_f32_e32 v16, -1.0, v14
	v_add_f32_e32 v17, 1.0, v14
	v_add_f32_e32 v18, 1.0, v16
	v_add_f32_e32 v19, -1.0, v17
	v_sub_f32_e32 v18, v14, v18
	v_sub_f32_e32 v14, v14, v19
	v_mul_f32_e32 v19, 0x3f317218, v6
	v_add_f32_e32 v18, v7, v18
	v_add_f32_e32 v7, v7, v14
	v_fma_f32 v14, v6, s6, -v19
	v_add_f32_e32 v20, v16, v18
	v_add_f32_e32 v21, v17, v7
	v_fmac_f32_e32 v14, 0xb102e308, v6
	v_sub_f32_e32 v6, v16, v20
	v_sub_f32_e32 v16, v17, v21
	v_rcp_f32_e32 v17, v21
	v_add_f32_e32 v22, v19, v14
	v_add_f32_e32 v7, v7, v16
	v_sub_f32_e32 v16, v22, v19
	v_sub_f32_e32 v14, v14, v16
	v_mul_f32_e32 v16, v20, v17
	v_add_f32_e32 v6, v18, v6
	v_mul_f32_e32 v18, v21, v16
	v_fma_f32 v19, v16, v21, -v18
	v_fmac_f32_e32 v19, v16, v7
	v_add_f32_e32 v23, v18, v19
	v_sub_f32_e32 v24, v20, v23
	v_sub_f32_e32 v18, v23, v18
	v_sub_f32_e32 v20, v20, v24
	v_sub_f32_e32 v18, v18, v19
	v_sub_f32_e32 v19, v20, v23
	v_add_f32_e32 v6, v6, v19
	v_add_f32_e32 v6, v18, v6
	v_add_f32_e32 v18, v24, v6
	v_mul_f32_e32 v19, v17, v18
	v_sub_f32_e32 v20, v24, v18
	v_mul_f32_e32 v23, v21, v19
	v_add_f32_e32 v6, v6, v20
	v_add_f32_e32 v20, v16, v19
	v_fma_f32 v21, v19, v21, -v23
	v_sub_f32_e32 v16, v20, v16
	v_fmac_f32_e32 v21, v19, v7
	v_sub_f32_e32 v7, v19, v16
	v_add_f32_e32 v16, v23, v21
	v_sub_f32_e32 v19, v16, v23
	v_sub_f32_e32 v23, v18, v16
	v_sub_f32_e32 v18, v18, v23
	v_sub_f32_e32 v16, v18, v16
	v_sub_f32_e32 v19, v19, v21
	v_add_f32_e32 v6, v6, v16
	v_add_f32_e32 v6, v19, v6
	v_add_f32_e32 v6, v23, v6
	v_mul_f32_e32 v6, v17, v6
	v_add_f32_e32 v6, v7, v6
	v_add_f32_e32 v7, v20, v6
	v_mul_f32_e32 v16, v7, v7
	v_fmamk_f32 v19, v16, 0x3e9b6dac, v9
	v_sub_f32_e32 v17, v7, v20
	v_ldexp_f32 v18, v7, 1
	v_mul_f32_e32 v7, v7, v16
	v_fmaak_f32 v16, v16, v19, 0x3f2aaada
	v_mul_f32_e32 v7, v7, v16
	v_add_f32_e32 v16, v18, v7
	v_sub_f32_e32 v6, v6, v17
	v_sub_f32_e32 v17, v16, v18
	v_ldexp_f32 v6, v6, 1
	v_sub_f32_e32 v7, v7, v17
	v_add_f32_e32 v6, v6, v7
	v_add_f32_e32 v7, v16, v6
	v_sub_f32_e32 v16, v7, v16
	v_add_f32_e32 v17, v22, v7
	v_sub_f32_e32 v6, v6, v16
	v_sub_f32_e32 v16, v17, v22
	v_sub_f32_e32 v18, v17, v16
	v_sub_f32_e32 v7, v7, v16
	v_add_f32_e32 v16, v14, v6
	v_sub_f32_e32 v18, v22, v18
	v_sub_f32_e32 v19, v16, v14
	v_add_f32_e32 v7, v7, v18
	v_sub_f32_e32 v18, v16, v19
	v_sub_f32_e32 v6, v6, v19
	v_sub_f32_e32 v14, v14, v18
	v_add_f32_e32 v7, v16, v7
	v_add_f32_e32 v6, v6, v14
	v_add_f32_e32 v14, v17, v7
	v_sub_f32_e32 v16, v14, v17
	v_sub_f32_e32 v7, v7, v16
	v_add_f32_e32 v6, v6, v7
	v_add_f32_e32 v6, v14, v6
	v_cmp_neq_f32_e32 vcc, s4, v2
	v_mov_b32_e32 v21, v3
	v_mov_b32_e32 v22, v3
	v_cndmask_b32_e32 v6, v8, v6, vcc
	v_cmp_lt_f32_e64 vcc, |v2|, s5
	v_mov_b32_e32 v23, v3
	v_mov_b32_e32 v24, v3
	v_cndmask_b32_e32 v2, v6, v2, vcc
	v_mul_f32_e32 v140, 0xbfb8aa3b, v2
	v_ldexp_f32 v2, v15, v11
	v_cmp_nlt_f32_e32 vcc, s8, v5
	s_mul_i32 s8, s1, 0x1200
	v_exp_f32_e64 v145, -v140
	v_cndmask_b32_e32 v2, 0, v2, vcc
	v_cmp_ngt_f32_e32 vcc, s9, v5
	v_mov_b32_e32 v97, v3
	v_readlane_b32 s27, v242, 11
	v_cndmask_b32_e32 v2, v8, v2, vcc
	v_add_f32_e32 v5, 1.0, v2
	v_add_f32_e32 v6, -1.0, v5
	v_sub_f32_e32 v7, v6, v5
	v_add_f32_e32 v7, 1.0, v7
	v_sub_f32_e32 v6, v2, v6
	v_add_f32_e32 v11, v6, v7
	v_frexp_mant_f32_e32 v14, v5
	v_cvt_f64_f32_e32 v[6:7], v5
	v_frexp_exp_i32_f64_e32 v6, v[6:7]
	v_cmp_gt_f32_e32 vcc, s10, v14
	v_readlane_b32 s28, v242, 12
	v_readlane_b32 s29, v242, 13
	v_subbrev_co_u32_e32 v6, vcc, 0, v6, vcc
	v_sub_u32_e32 v7, 0, v6
	v_ldexp_f32 v5, v5, v7
	v_ldexp_f32 v7, v11, v7
	v_add_f32_e32 v11, -1.0, v5
	v_add_f32_e32 v16, 1.0, v5
	v_add_f32_e32 v14, 1.0, v11
	v_add_f32_e32 v17, -1.0, v16
	v_sub_f32_e32 v14, v5, v14
	v_sub_f32_e32 v5, v5, v17
	v_add_f32_e32 v5, v7, v5
	v_add_f32_e32 v14, v7, v14
	v_add_f32_e32 v7, v16, v5
	v_rcp_f32_e32 v17, v7
	v_add_f32_e32 v15, v11, v14
	v_sub_f32_e32 v11, v11, v15
	v_add_f32_e32 v11, v14, v11
	v_sub_f32_e32 v14, v16, v7
	v_add_f32_e32 v5, v5, v14
	v_mul_f32_e32 v14, v15, v17
	v_mul_f32_e32 v16, v7, v14
	v_fma_f32 v18, v14, v7, -v16
	v_fmac_f32_e32 v18, v14, v5
	v_add_f32_e32 v19, v16, v18
	v_sub_f32_e32 v20, v15, v19
	v_sub_f32_e32 v15, v15, v20
	v_sub_f32_e32 v16, v19, v16
	v_sub_f32_e32 v15, v15, v19
	v_add_f32_e32 v11, v11, v15
	v_sub_f32_e32 v15, v16, v18
	v_add_f32_e32 v11, v15, v11
	v_add_f32_e32 v15, v20, v11
	v_mul_f32_e32 v16, v17, v15
	v_mul_f32_e32 v18, v7, v16
	v_fma_f32 v7, v16, v7, -v18
	v_fmac_f32_e32 v7, v16, v5
	v_sub_f32_e32 v5, v20, v15
	v_add_f32_e32 v5, v11, v5
	v_add_f32_e32 v11, v18, v7
	v_sub_f32_e32 v19, v15, v11
	v_sub_f32_e32 v15, v15, v19
	v_sub_f32_e32 v18, v11, v18
	v_sub_f32_e32 v11, v15, v11
	v_add_f32_e32 v5, v5, v11
	v_sub_f32_e32 v7, v18, v7
	v_add_f32_e32 v5, v7, v5
	v_add_f32_e32 v7, v14, v16
	v_add_f32_e32 v5, v19, v5
	v_sub_f32_e32 v11, v7, v14
	v_mul_f32_e32 v5, v17, v5
	v_sub_f32_e32 v11, v16, v11
	v_add_f32_e32 v5, v11, v5
	v_cvt_f32_i32_e32 v6, v6
	v_add_f32_e32 v11, v7, v5
	v_mul_f32_e32 v14, v11, v11
	v_fmac_f32_e32 v9, 0x3e9b6dac, v14
	v_fmac_f32_e32 v10, v14, v9
	v_mul_f32_e32 v9, 0x3f317218, v6
	v_fma_f32 v15, v6, s6, -v9
	v_fmac_f32_e32 v15, 0xb102e308, v6
	v_sub_f32_e32 v6, v11, v7
	v_sub_f32_e32 v5, v5, v6
	v_add_f32_e32 v6, v9, v15
	v_sub_f32_e32 v7, v6, v9
	v_ldexp_f32 v9, v11, 1
	v_mul_f32_e32 v11, v11, v14
	v_mul_f32_e32 v10, v11, v10
	v_add_f32_e32 v11, v9, v10
	v_sub_f32_e32 v9, v11, v9
	v_ldexp_f32 v5, v5, 1
	v_sub_f32_e32 v9, v10, v9
	v_add_f32_e32 v5, v5, v9
	v_add_f32_e32 v9, v11, v5
	v_sub_f32_e32 v10, v9, v11
	v_sub_f32_e32 v5, v5, v10
	v_add_f32_e32 v10, v6, v9
	v_sub_f32_e32 v11, v10, v6
	v_sub_f32_e32 v14, v10, v11
	v_sub_f32_e32 v7, v15, v7
	v_sub_f32_e32 v6, v6, v14
	v_sub_f32_e32 v9, v9, v11
	v_add_f32_e32 v6, v9, v6
	v_add_f32_e32 v9, v7, v5
	v_sub_f32_e32 v11, v9, v7
	v_sub_f32_e32 v14, v9, v11
	v_sub_f32_e32 v7, v7, v14
	v_sub_f32_e32 v5, v5, v11
	v_add_f32_e32 v6, v9, v6
	v_add_f32_e32 v5, v5, v7
	v_add_f32_e32 v7, v10, v6
	v_sub_f32_e32 v9, v7, v10
	v_sub_f32_e32 v6, v6, v9
	v_add_f32_e32 v5, v5, v6
	v_add_f32_e32 v5, v7, v5
	v_cmp_neq_f32_e32 vcc, s4, v2
	s_lshl_b32 s4, s0, 7
	v_ashrrev_i32_e32 v15, 4, v4
	v_cndmask_b32_e32 v5, v8, v5, vcc
	v_cmp_lt_f32_e64 vcc, |v2|, s5
	s_lshl_b32 s5, s1, 5
	s_add_u32 s0, s68, s16
	v_cndmask_b32_e32 v2, v5, v2, vcc
	v_mul_f32_e32 v149, 0xbfb8aa3b, v2
	v_mul_f32_e32 v2, 0x80000000, v140
	v_exp_f32_e32 v147, v2
	v_mul_f32_e32 v2, 0, v149
	v_exp_f32_e32 v148, v2
	v_mul_f32_e32 v2, -2.0, v140
	v_exp_f32_e32 v143, v2
	v_add_f32_e32 v2, v149, v149
	v_exp_f32_e32 v144, v2
	v_mul_f32_e32 v2, 0xc0400000, v140
	v_exp_f32_e32 v142, v2
	v_mul_f32_e32 v2, 0x40400000, v149
	v_exp_f32_e32 v141, v2
	v_or_b32_e32 v2, s5, v12
	v_add_u32_e32 v5, s3, v2
	s_addc_u32 s1, s69, 0
	v_and_b32_e32 v2, 48, v4
	v_lshl_add_u64 v[6:7], s[0:1], 0, v[2:3]
	v_mad_i64_i32 v[8:9], s[6:7], v5, s18, v[6:7]
	v_or_b32_e32 v5, 16, v5
	v_mad_i64_i32 v[6:7], s[6:7], v5, s18, v[6:7]
	global_load_dwordx4 v[90:93], v[8:9], off
	global_load_dwordx4 v[86:89], v[8:9], off offset:64
	global_load_dwordx4 v[82:85], v[8:9], off offset:128
	global_load_dwordx4 v[78:81], v[8:9], off offset:192
	global_load_dwordx4 v[58:61], v[6:7], off
	global_load_dwordx4 v[54:57], v[6:7], off offset:64
	global_load_dwordx4 v[46:49], v[6:7], off offset:128
	global_load_dwordx4 v[42:45], v[6:7], off offset:192
	v_add_u32_e32 v16, s3, v15
	v_mov_b64_e32 v[6:7], s[68:69]
	v_mad_i64_i32 v[8:9], s[6:7], v16, s18, v[6:7]
	v_lshlrev_b32_e32 v10, 4, v4
	v_lshl_add_u64 v[8:9], v[8:9], 0, s[16:17]
	v_and_b32_e32 v10, 0xf0, v10
	v_mov_b32_e32 v11, v3
	v_lshl_add_u64 v[8:9], v[8:9], 0, v[10:11]
	global_load_dwordx4 v[98:101], v[8:9], off offset:1024
	global_load_dwordx4 v[102:105], v[8:9], off offset:2048
	v_add_u32_e32 v8, 0x200, v4
	v_ashrrev_i32_e32 v8, 4, v8
	v_add_u32_e32 v9, s3, v8
	v_mad_i64_i32 v[6:7], s[6:7], v9, s18, v[6:7]
	v_lshl_add_u64 v[6:7], v[6:7], 0, s[16:17]
	v_lshl_add_u64 v[6:7], v[6:7], 0, v[10:11]
	global_load_dwordx4 v[106:109], v[6:7], off offset:1024
	global_load_dwordx4 v[110:113], v[6:7], off offset:2048
	v_exp_f32_e32 v146, v149
	v_lshlrev_b32_e32 v14, 3, v13
	v_lshlrev_b32_e32 v5, 3, v4
	v_lshlrev_b32_e32 v13, 2, v13
	v_bfe_u32 v4, v4, 2, 2
	s_add_i32 s6, s8, 0
	v_add_u32_e32 v6, 0, v10
	v_add_u32_e32 v7, 0, v2
	v_sub_u32_e32 v17, v12, v13
	v_or_b32_e32 v4, v14, v4
	v_and_b32_e32 v5, 24, v5
	s_movk_i32 s8, 0x110
	v_add_u32_e32 v150, s5, v17
	v_add_u32_e32 v17, s6, v14
	v_add_u32_e32 v2, s6, v2
	v_add_u32_e32 v5, 0, v5
	v_mad_u64_u32 v[136:137], s[6:7], v15, s8, v[6:7]
	v_mad_u64_u32 v[134:135], s[6:7], v8, s8, v[6:7]
	v_mul_u32_u24_e32 v6, 0x110, v12
	v_mul_u32_u24_e32 v8, 0x90, v12
	v_mul_u32_u24_e32 v4, 0x110, v4
	v_lshl_add_u64 v[138:139], s[0:1], 0, v[10:11]
	v_sub_u32_e32 v10, v13, v12
	v_subrev_u32_e32 v153, s5, v10
	v_add_u32_e32 v154, 64, v9
	v_add_u32_e32 v155, 64, v16
	s_movk_i32 s16, 0xffef
	v_add_u32_e32 v152, v7, v6
	v_add_u32_e32 v151, v17, v8
	v_add_u32_e32 v137, v2, v8
	v_add_u32_e32 v135, v5, v4
	v_mov_b32_e32 v156, v150
	v_mov_b32_e32 v2, v3
	v_mov_b32_e32 v4, v3
	v_mov_b32_e32 v5, v3
	v_mov_b32_e32 v6, v3
	v_mov_b32_e32 v7, v3
	v_mov_b32_e32 v8, v3
	v_mov_b32_e32 v9, v3
	v_mov_b32_e32 v10, v3
	v_mov_b32_e32 v12, v3
	v_mov_b32_e32 v13, v3
	v_mov_b32_e32 v14, v3
	v_mov_b32_e32 v15, v3
	v_mov_b32_e32 v16, v3
	v_mov_b32_e32 v17, v3
	v_mov_b32_e32 v18, v3
	v_mov_b32_e32 v19, v3
	v_mov_b32_e32 v20, v3
	v_readlane_b32 s30, v242, 14
	v_readlane_b32 s31, v242, 15
